# out phase: unit kind order rotated by workgroup index ((k+w)%3) as in the local phase
# speedup vs baseline: 1.0442x; 1.0101x over previous
.LBB0_690:
	s_cmpk_eq_i32 s8, 0x100
	s_cselect_b64 s[100:101], -1, 0
	s_mul_i32 s9, s8, 3
	v_readlane_b32 s0, v255, 0
	s_cmp_ge_i32 s0, s9
	s_mov_b32 s52, 0x10800
	s_mov_b32 s53, 0x8100
	s_mov_b32 s59, 0x3195000
	s_cbranch_scc1 .LBB0_1159
	v_cvt_f32_u32_e32 v0, s8
	v_readlane_b32 s0, v255, 25
	s_sub_i32 s4, 0, s8
	v_readlane_b32 s1, v255, 26
	v_rcp_iflag_f32_e32 v0, v0
	s_mov_b32 s2, s0
	s_lshl_b32 s48, s0, 8
	s_lshl_b32 s10, s0, 10
	v_mul_f32_e32 v0, 0x4f7ffffe, v0
	v_cvt_u32_f32_e32 v0, v0
	s_lshl_b32 s24, s0, 1
	s_lshl_b32 s0, s0, 9
	s_mov_b32 s1, s49
	v_readfirstlane_b32 s5, v0
	s_mul_i32 s4, s4, s5
	s_lshl_b32 s14, s2, 11
	s_lshl_b32 s25, s2, 3
	s_lshl_b32 s26, s2, 2
	s_lshl_b32 s27, s2, 12
	s_lshl_b32 s2, s2, 6
	s_mov_b32 s3, s49
	s_mul_hi_u32 s4, s5, s4
	s_mov_b32 s11, s49
	s_mov_b32 s15, s49
	s_add_i32 s28, s5, s4
	s_lshl_b64 s[16:17], s[2:3], 2
	s_lshl_b64 s[18:19], s[0:1], 2
	v_readlane_b32 s29, v255, 0
	s_cmp_eq_u32 s9, 0x300
	s_cbranch_scc0 .Lrot_o_e
	s_cmpk_lg_i32 s36, 0x100
	s_cbranch_scc1 .Lrot_o_e
	s_mul_i32 s0, s29, 171
	s_lshr_b32 s0, s0, 9
	s_mul_i32 s0, s0, 3
	s_sub_i32 s0, s29, s0
	s_lshl_b32 s0, s0, 8
	s_add_i32 s29, s29, s0
.Lrot_o_e:
	s_branch .LBB0_694
.LBB0_692:
	s_or_b64 exec, exec, s[0:1]
	s_waitcnt lgkmcnt(0)
	s_barrier
	ds_read2_b64 v[0:3], v129 offset0:26 offset1:29
	v_lshlrev_b32_e32 v4, 3, v130
	v_ashrrev_i32_e32 v7, 5, v130
	v_and_b32_e32 v6, 0xf8, v4
	v_add_u32_e32 v50, s20, v7
	s_waitcnt lgkmcnt(0)
	v_mad_i64_i32 v[12:13], s[0:1], v50, s86, v[2:3]
	v_lshlrev_b32_e32 v128, 1, v6
	v_lshl_add_u64 v[4:5], v[12:13], 0, v[128:129]
	s_mov_b32 s4, 0x3196000
	v_add_co_u32_e32 v4, vcc, s4, v4
	v_lshlrev_b32_e32 v9, 2, v6
	s_nop 0
	v_addc_co_u32_e32 v5, vcc, 0, v5, vcc
	global_load_dwordx4 v[14:17], v[4:5], off offset:1616 nt
	v_add_u32_e32 v4, 0x200, v130
	v_ashrrev_i32_e32 v22, 5, v4
	v_add_u32_e32 v51, s20, v22
	v_mad_i64_i32 v[10:11], s[0:1], v51, s86, v[2:3]
	v_lshl_add_u64 v[4:5], v[10:11], 0, v[128:129]
	v_add_co_u32_e32 v4, vcc, s4, v4
	s_lshl_b64 s[0:1], s[48:49], 2
	s_nop 0
	v_addc_co_u32_e32 v5, vcc, 0, v5, vcc
	global_load_dwordx4 v[18:21], v[4:5], off offset:1616 nt
	v_lshl_add_u64 v[0:1], v[0:1], 0, s[0:1]
	v_readlane_b32 s2, v255, 17
	v_readfirstlane_b32 s0, v0
	v_readfirstlane_b32 s1, v1
	v_add_u32_e32 v8, s2, v9
	v_mad_u64_u32 v[4:5], s[2:3], v7, s33, v[8:9]
	v_mad_u64_u32 v[26:27], s[2:3], v22, s33, v[8:9]
	ds_read2_b32 v[28:29], v4 offset0:6 offset1:7
	ds_read2_b32 v[30:31], v4 offset0:4 offset1:5
	ds_read2_b32 v[32:33], v4 offset0:2 offset1:3
	ds_read2_b32 v[34:35], v4 offset1:1
	global_load_dwordx4 v[4:7], v9, s[0:1] offset:16
	global_load_dwordx4 v[22:25], v9, s[0:1]
	s_mov_b32 s2, 0x358637bd
	s_mov_b32 s6, 0x3b800000
	s_mov_b32 s12, 0x3196000
	s_waitcnt vmcnt(3)
	v_lshlrev_b32_e32 v0, 16, v17
	v_and_b32_e32 v1, 0xffff0000, v17
	v_lshlrev_b32_e32 v36, 16, v16
	v_and_b32_e32 v37, 0xffff0000, v16
	v_lshlrev_b32_e32 v16, 16, v15
	v_and_b32_e32 v17, 0xffff0000, v15
	v_lshlrev_b32_e32 v38, 16, v14
	v_and_b32_e32 v39, 0xffff0000, v14
	v_mul_f32_e32 v40, 0xbfb8aa3b, v36
	v_mul_f32_e32 v41, 0xbfb8aa3b, v37
	v_mul_f32_e32 v42, 0xbfb8aa3b, v16
	v_mul_f32_e32 v43, 0xbfb8aa3b, v17
	v_mul_f32_e32 v44, 0xbfb8aa3b, v38
	v_mul_f32_e32 v45, 0xbfb8aa3b, v39
	v_exp_f32_e32 v40, v40
	v_exp_f32_e32 v41, v41
	v_exp_f32_e32 v42, v42
	v_exp_f32_e32 v43, v43
	v_exp_f32_e32 v44, v44
	v_exp_f32_e32 v45, v45
	s_waitcnt vmcnt(2)
	v_and_b32_e32 v15, 0xffff0000, v21
	v_mul_f32_e32 v47, 0xbfb8aa3b, v15
	v_lshlrev_b32_e32 v14, 16, v21
	v_mul_f32_e32 v21, 0xbfb8aa3b, v0
	v_exp_f32_e32 v48, v47
	v_add_f32_e32 v47, 1.0, v40
	v_add_f32_e32 v49, 1.0, v41
	v_add_f32_e32 v52, 1.0, v42
	v_add_f32_e32 v53, 1.0, v43
	v_mul_f32_e32 v46, 0xbfb8aa3b, v14
	v_exp_f32_e32 v21, v21
	v_add_f32_e32 v54, 1.0, v44
	v_add_f32_e32 v55, 1.0, v45
	v_rcp_f32_e32 v42, v47
	v_rcp_f32_e32 v43, v49
	v_rcp_f32_e32 v44, v52
	v_rcp_f32_e32 v45, v53
	v_mul_f32_e32 v27, 0xbfb8aa3b, v1
	v_exp_f32_e32 v46, v46
	v_exp_f32_e32 v27, v27
	v_add_f32_e32 v21, 1.0, v21
	v_pk_mul_f32 v[36:37], v[42:43], v[36:37]
	v_pk_mul_f32 v[16:17], v[44:45], v[16:17]
	v_lshlrev_b32_e32 v42, 16, v20
	v_and_b32_e32 v43, 0xffff0000, v20
	v_add_f32_e32 v56, 1.0, v46
	v_rcp_f32_e32 v40, v21
	s_waitcnt lgkmcnt(1)
	v_pk_mul_f32 v[32:33], v[32:33], v[16:17]
	v_add_f32_e32 v17, 1.0, v48
	v_mul_f32_e32 v20, 0xbfb8aa3b, v42
	v_mul_f32_e32 v21, 0xbfb8aa3b, v43
	v_add_f32_e32 v27, 1.0, v27
	v_rcp_f32_e32 v16, v56
	v_rcp_f32_e32 v17, v17
	v_exp_f32_e32 v20, v20
	v_exp_f32_e32 v21, v21
	v_rcp_f32_e32 v41, v27
	v_pk_mul_f32 v[14:15], v[16:17], v[14:15]
	v_add_f32_e32 v16, 1.0, v20
	v_add_f32_e32 v17, 1.0, v21
	v_pk_mul_f32 v[0:1], v[40:41], v[0:1]
	ds_read2_b32 v[40:41], v26 offset0:6 offset1:7
	ds_read2_b32 v[20:21], v26 offset0:4 offset1:5
	v_rcp_f32_e32 v16, v16
	v_rcp_f32_e32 v17, v17
	v_rcp_f32_e32 v46, v54
	v_rcp_f32_e32 v47, v55
	v_lshlrev_b32_e32 v48, 16, v18
	v_pk_mul_f32 v[16:17], v[16:17], v[42:43]
	ds_read2_b32 v[42:43], v26 offset0:2 offset1:3
	s_waitcnt lgkmcnt(1)
	v_pk_mul_f32 v[16:17], v[20:21], v[16:17]
	v_lshlrev_b32_e32 v20, 16, v19
	v_and_b32_e32 v21, 0xffff0000, v19
	v_mul_f32_e32 v19, 0xbfb8aa3b, v20
	v_exp_f32_e32 v19, v19
	v_mul_f32_e32 v27, 0xbfb8aa3b, v21
	v_exp_f32_e32 v27, v27
	v_pk_mul_f32 v[38:39], v[46:47], v[38:39]
	v_add_f32_e32 v19, 1.0, v19
	v_rcp_f32_e32 v46, v19
	v_add_f32_e32 v19, 1.0, v27
	v_and_b32_e32 v49, 0xffff0000, v18
	v_rcp_f32_e32 v47, v19
	v_mul_f32_e32 v19, 0xbfb8aa3b, v48
	v_mul_f32_e32 v18, 0xbfb8aa3b, v49
	v_exp_f32_e32 v19, v19
	v_exp_f32_e32 v52, v18
	ds_read2_b32 v[26:27], v26 offset1:1
	v_pk_mul_f32 v[34:35], v[34:35], v[38:39]
	v_add_f32_e32 v18, 1.0, v19
	v_add_f32_e32 v19, 1.0, v52
	v_rcp_f32_e32 v18, v18
	v_rcp_f32_e32 v19, v19
	v_pk_mul_f32 v[20:21], v[46:47], v[20:21]
	v_pk_mul_f32 v[38:39], v[32:33], v[32:33]
	s_waitcnt lgkmcnt(1)
	v_pk_mul_f32 v[42:43], v[42:43], v[20:21]
	v_pk_mul_f32 v[18:19], v[18:19], v[48:49]
	v_pk_mul_f32 v[20:21], v[42:43], v[42:43]
	s_waitcnt lgkmcnt(0)
	v_pk_mul_f32 v[46:47], v[26:27], v[18:19]
	v_mov_b32_e32 v27, v35
	v_mov_b32_e32 v26, v47
	v_mov_b32_e32 v18, v46
	v_mov_b32_e32 v19, v34
	v_pk_mul_f32 v[26:27], v[26:27], v[26:27]
	v_pk_mul_f32 v[30:31], v[30:31], v[36:37]
	v_pk_fma_f32 v[18:19], v[18:19], v[18:19], v[26:27]
	v_mov_b32_e32 v26, v20
	v_mov_b32_e32 v27, v38
	v_pk_mul_f32 v[36:37], v[30:31], v[30:31]
	v_pk_mul_f32 v[44:45], v[16:17], v[16:17]
	v_pk_add_f32 v[18:19], v[26:27], v[18:19]
	v_mov_b32_e32 v38, v21
	v_pk_mul_f32 v[28:29], v[28:29], v[0:1]
	v_pk_mul_f32 v[14:15], v[40:41], v[14:15]
	v_pk_add_f32 v[18:19], v[38:39], v[18:19]
	v_mov_b32_e32 v20, v44
	v_mov_b32_e32 v21, v36
	v_pk_mul_f32 v[0:1], v[28:29], v[28:29]
	v_pk_mul_f32 v[40:41], v[14:15], v[14:15]
	v_pk_add_f32 v[18:19], v[20:21], v[18:19]
	v_mov_b32_e32 v36, v45
	v_pk_add_f32 v[18:19], v[36:37], v[18:19]
	v_mov_b32_e32 v20, v40
	v_mov_b32_e32 v21, v0
	v_pk_add_f32 v[18:19], v[20:21], v[18:19]
	v_mov_b32_e32 v0, v41
	v_pk_add_f32 v[0:1], v[0:1], v[18:19]
	ds_bpermute_b32 v19, v199, v1
	ds_bpermute_b32 v18, v199, v0
	s_waitcnt lgkmcnt(0)
	v_pk_add_f32 v[0:1], v[0:1], v[18:19]
	ds_bpermute_b32 v19, v198, v1
	ds_bpermute_b32 v18, v198, v0
	s_waitcnt lgkmcnt(0)
	v_pk_add_f32 v[0:1], v[0:1], v[18:19]
	ds_bpermute_b32 v19, v197, v1
	ds_bpermute_b32 v18, v197, v0
	s_waitcnt lgkmcnt(0)
	v_pk_add_f32 v[0:1], v[0:1], v[18:19]
	ds_bpermute_b32 v19, v196, v1
	ds_bpermute_b32 v18, v196, v0
	s_waitcnt lgkmcnt(0)
	v_pk_add_f32 v[0:1], v[0:1], v[18:19]
	ds_bpermute_b32 v19, v195, v1
	ds_bpermute_b32 v18, v195, v0
	s_waitcnt lgkmcnt(0)
	v_pk_add_f32 v[18:19], v[0:1], v[18:19]
	v_mov_b64_e32 v[0:1], s[2:3]
	v_pk_fma_f32 v[36:37], v[18:19], s[6:7], v[0:1] op_sel_hi:[1,0,0]
	v_mad_i64_i32 v[12:13], s[2:3], v50, s56, v[12:13]
	v_mul_f32_e32 v18, 0x4b800000, v37
	v_cmp_gt_f32_e32 vcc, s82, v37
	v_lshl_add_u64 v[12:13], v[12:13], 0, v[128:129]
	s_nop 0
	v_cndmask_b32_e32 v18, v37, v18, vcc
	v_rsq_f32_e32 v18, v18
	s_nop 0
	v_mul_f32_e32 v19, 0x45800000, v18
	v_cndmask_b32_e32 v26, v18, v19, vcc
	v_pk_mul_f32 v[18:19], v[34:35], v[26:27] op_sel_hi:[1,0]
	v_pk_mul_f32 v[20:21], v[32:33], v[26:27] op_sel_hi:[1,0]
	s_waitcnt vmcnt(0)
	v_pk_mul_f32 v[18:19], v[22:23], v[18:19]
	v_pk_mul_f32 v[20:21], v[24:25], v[20:21]
	v_cvt_pk_bf16_f32 v18, v18, v19
	v_cvt_pk_bf16_f32 v19, v20, v21
	v_pk_mul_f32 v[20:21], v[30:31], v[26:27] op_sel_hi:[1,0]
	s_nop 0
	v_pk_mul_f32 v[4:5], v[4:5], v[20:21]
	s_nop 0
	v_cvt_pk_bf16_f32 v20, v4, v5
	v_pk_mul_f32 v[4:5], v[28:29], v[26:27] op_sel_hi:[1,0]
	s_nop 0
	v_pk_mul_f32 v[4:5], v[6:7], v[4:5]
	s_nop 0
	v_cvt_pk_bf16_f32 v21, v4, v5
	v_add_co_u32_e32 v4, vcc, s44, v12
	s_nop 1
	v_addc_co_u32_e32 v5, vcc, 0, v13, vcc
	global_store_dwordx4 v[4:5], v[18:21], off offset:1536
	global_load_dwordx4 v[18:21], v9, s[0:1]
	s_nop 0
	global_load_dwordx4 v[22:25], v9, s[0:1] offset:16
	v_add_u32_e32 v4, 0x400, v130
	v_ashrrev_i32_e32 v34, 5, v4
	v_add_u32_e32 v50, s20, v34
	v_mad_i64_i32 v[4:5], s[2:3], v50, s86, v[2:3]
	v_lshl_add_u64 v[6:7], v[4:5], 0, v[128:129]
	v_add_co_u32_e32 v6, vcc, s4, v6
	v_mad_i64_i32 v[4:5], s[2:3], v50, s56, v[4:5]
	s_nop 0
	v_addc_co_u32_e32 v7, vcc, 0, v7, vcc
	global_load_dwordx4 v[26:29], v[6:7], off offset:1616 nt
	v_mul_f32_e32 v6, 0x4b800000, v36
	v_cmp_gt_f32_e32 vcc, s82, v36
	s_waitcnt vmcnt(0)
	v_lshlrev_b32_e32 v38, 16, v26
	v_cndmask_b32_e32 v6, v36, v6, vcc
	v_rsq_f32_e32 v6, v6
	v_and_b32_e32 v39, 0xffff0000, v26
	v_mul_f32_e32 v26, 0xbfb8aa3b, v39
	v_mul_f32_e32 v7, 0x45800000, v6
	v_cndmask_b32_e32 v6, v6, v7, vcc
	v_pk_mul_f32 v[12:13], v[46:47], v[6:7] op_sel_hi:[1,0]
	v_add_u32_e32 v7, 0x600, v130
	v_ashrrev_i32_e32 v40, 5, v7
	v_add_u32_e32 v52, s20, v40
	v_mad_i64_i32 v[2:3], s[2:3], v52, s86, v[2:3]
	v_pk_mul_f32 v[12:13], v[18:19], v[12:13]
	v_lshl_add_u64 v[18:19], v[2:3], 0, v[128:129]
	v_add_co_u32_e32 v18, vcc, s4, v18
	s_nop 1
	v_addc_co_u32_e32 v19, vcc, 0, v19, vcc
	global_load_dwordx4 v[30:33], v[18:19], off offset:1616 nt
	v_cvt_pk_bf16_f32 v18, v12, v13
	v_pk_mul_f32 v[12:13], v[42:43], v[6:7] op_sel_hi:[1,0]
	s_waitcnt vmcnt(0)
	v_lshlrev_b32_e32 v42, 16, v32
	v_pk_mul_f32 v[12:13], v[20:21], v[12:13]
	v_and_b32_e32 v43, 0xffff0000, v32
	v_cvt_pk_bf16_f32 v19, v12, v13
	v_pk_mul_f32 v[12:13], v[16:17], v[6:7] op_sel_hi:[1,0]
	v_pk_mul_f32 v[6:7], v[14:15], v[6:7] op_sel_hi:[1,0]
	v_pk_mul_f32 v[12:13], v[22:23], v[12:13]
	v_pk_mul_f32 v[6:7], v[24:25], v[6:7]
	v_cvt_pk_bf16_f32 v20, v12, v13
	v_cvt_pk_bf16_f32 v21, v6, v7
	v_mad_i64_i32 v[6:7], s[2:3], v51, s56, v[10:11]
	v_lshlrev_b32_e32 v10, 16, v29
	v_and_b32_e32 v11, 0xffff0000, v29
	v_mul_f32_e32 v12, 0xbfb8aa3b, v10
	v_mul_f32_e32 v13, 0xbfb8aa3b, v11
	v_exp_f32_e32 v12, v12
	v_exp_f32_e32 v13, v13
	v_lshl_add_u64 v[6:7], v[6:7], 0, v[128:129]
	v_add_co_u32_e32 v6, vcc, s44, v6
	v_lshlrev_b32_e32 v48, 16, v30
	s_nop 0
	v_addc_co_u32_e32 v7, vcc, 0, v7, vcc
	global_store_dwordx4 v[6:7], v[18:21], off offset:1536
	v_add_f32_e32 v6, 1.0, v12
	v_add_f32_e32 v7, 1.0, v13
	v_rcp_f32_e32 v6, v6
	v_rcp_f32_e32 v7, v7
	v_mad_u64_u32 v[18:19], s[2:3], v34, s33, v[8:9]
	v_lshlrev_b32_e32 v20, 16, v28
	v_and_b32_e32 v21, 0xffff0000, v28
	ds_read2_b32 v[12:13], v18 offset0:6 offset1:7
	ds_read2_b32 v[22:23], v18 offset0:4 offset1:5
	v_pk_mul_f32 v[6:7], v[6:7], v[10:11]
	v_mul_f32_e32 v10, 0xbfb8aa3b, v20
	v_mul_f32_e32 v11, 0xbfb8aa3b, v21
	v_exp_f32_e32 v10, v10
	v_exp_f32_e32 v11, v11
	s_waitcnt lgkmcnt(1)
	v_pk_mul_f32 v[24:25], v[12:13], v[6:7]
	v_and_b32_e32 v49, 0xffff0000, v30
	v_add_f32_e32 v6, 1.0, v10
	v_add_f32_e32 v7, 1.0, v11
	v_rcp_f32_e32 v6, v6
	v_rcp_f32_e32 v7, v7
	global_load_dwordx4 v[10:13], v9, s[0:1] offset:16
	global_load_dwordx4 v[14:17], v9, s[0:1]
	v_pk_mul_f32 v[28:29], v[24:25], v[24:25]
	v_pk_mul_f32 v[6:7], v[6:7], v[20:21]
	s_waitcnt lgkmcnt(0)
	v_pk_mul_f32 v[6:7], v[22:23], v[6:7]
	v_lshlrev_b32_e32 v22, 16, v27
	v_and_b32_e32 v23, 0xffff0000, v27
	v_mul_f32_e32 v19, 0xbfb8aa3b, v22
	v_exp_f32_e32 v19, v19
	v_mul_f32_e32 v27, 0xbfb8aa3b, v23
	v_exp_f32_e32 v27, v27
	ds_read2_b32 v[20:21], v18 offset0:2 offset1:3
	v_add_f32_e32 v19, 1.0, v19
	v_rcp_f32_e32 v36, v19
	v_add_f32_e32 v19, 1.0, v27
	v_rcp_f32_e32 v37, v19
	v_mul_f32_e32 v19, 0xbfb8aa3b, v38
	v_exp_f32_e32 v19, v19
	v_exp_f32_e32 v27, v26
	v_pk_mul_f32 v[22:23], v[36:37], v[22:23]
	v_lshlrev_b32_e32 v36, 16, v33
	v_add_f32_e32 v19, 1.0, v19
	v_add_f32_e32 v27, 1.0, v27
	v_rcp_f32_e32 v26, v19
	ds_read2_b32 v[18:19], v18 offset1:1
	v_rcp_f32_e32 v27, v27
	v_and_b32_e32 v37, 0xffff0000, v33
	s_waitcnt lgkmcnt(1)
	v_pk_mul_f32 v[20:21], v[20:21], v[22:23]
	v_pk_mul_f32 v[34:35], v[6:7], v[6:7]
	v_pk_mul_f32 v[26:27], v[26:27], v[38:39]
	v_pk_mul_f32 v[22:23], v[20:21], v[20:21]
	s_waitcnt lgkmcnt(0)
	v_pk_mul_f32 v[18:19], v[18:19], v[26:27]
	v_mad_u64_u32 v[26:27], s[2:3], v40, s33, v[8:9]
	v_mul_f32_e32 v8, 0xbfb8aa3b, v36
	v_exp_f32_e32 v8, v8
	v_mul_f32_e32 v27, 0xbfb8aa3b, v37
	v_exp_f32_e32 v27, v27
	ds_read2_b32 v[40:41], v26 offset0:6 offset1:7
	v_add_f32_e32 v8, 1.0, v8
	v_rcp_f32_e32 v38, v8
	v_add_f32_e32 v8, 1.0, v27
	v_rcp_f32_e32 v39, v8
	v_mul_f32_e32 v8, 0xbfb8aa3b, v42
	v_exp_f32_e32 v8, v8
	v_mul_f32_e32 v27, 0xbfb8aa3b, v43
	v_exp_f32_e32 v27, v27
	v_pk_mul_f32 v[32:33], v[38:39], v[36:37]
	v_add_f32_e32 v8, 1.0, v8
	v_rcp_f32_e32 v36, v8
	v_add_f32_e32 v8, 1.0, v27
	v_rcp_f32_e32 v37, v8
	ds_read2_b32 v[38:39], v26 offset0:4 offset1:5
	s_waitcnt lgkmcnt(1)
	v_pk_mul_f32 v[32:33], v[40:41], v[32:33]
	v_pk_mul_f32 v[36:37], v[36:37], v[42:43]
	ds_read2_b32 v[42:43], v26 offset0:2 offset1:3
	s_waitcnt lgkmcnt(1)
	v_pk_mul_f32 v[36:37], v[38:39], v[36:37]
	v_lshlrev_b32_e32 v38, 16, v31
	v_and_b32_e32 v39, 0xffff0000, v31
	v_mul_f32_e32 v8, 0xbfb8aa3b, v38
	v_exp_f32_e32 v8, v8
	v_mul_f32_e32 v27, 0xbfb8aa3b, v39
	v_exp_f32_e32 v27, v27
	v_pk_mul_f32 v[44:45], v[36:37], v[36:37]
	v_add_f32_e32 v8, 1.0, v8
	v_rcp_f32_e32 v46, v8
	v_add_f32_e32 v8, 1.0, v27
	v_rcp_f32_e32 v47, v8
	v_mul_f32_e32 v8, 0xbfb8aa3b, v48
	v_exp_f32_e32 v8, v8
	v_mul_f32_e32 v27, 0xbfb8aa3b, v49
	v_exp_f32_e32 v31, v27
	ds_read2_b32 v[26:27], v26 offset1:1
	v_add_f32_e32 v8, 1.0, v8
	v_rcp_f32_e32 v30, v8
	v_add_f32_e32 v8, 1.0, v31
	v_rcp_f32_e32 v31, v8
	v_pk_mul_f32 v[38:39], v[46:47], v[38:39]
	v_mov_b32_e32 v47, v19
	s_waitcnt lgkmcnt(1)
	v_pk_mul_f32 v[38:39], v[42:43], v[38:39]
	v_pk_mul_f32 v[30:31], v[30:31], v[48:49]
	v_pk_mul_f32 v[42:43], v[38:39], v[38:39]
	s_waitcnt lgkmcnt(0)
	v_pk_mul_f32 v[26:27], v[26:27], v[30:31]
	v_mov_b32_e32 v31, v18
	v_mov_b32_e32 v46, v27
	v_mov_b32_e32 v30, v26
	v_pk_mul_f32 v[46:47], v[46:47], v[46:47]
	v_pk_mul_f32 v[40:41], v[32:33], v[32:33]
	v_pk_fma_f32 v[30:31], v[30:31], v[30:31], v[46:47]
	v_mov_b32_e32 v46, v42
	v_mov_b32_e32 v47, v22
	v_pk_add_f32 v[30:31], v[46:47], v[30:31]
	v_mov_b32_e32 v22, v43
	v_pk_add_f32 v[22:23], v[22:23], v[30:31]
	v_mov_b32_e32 v30, v44
	v_mov_b32_e32 v31, v34
	v_pk_add_f32 v[22:23], v[30:31], v[22:23]
	v_mov_b32_e32 v34, v45
	v_pk_add_f32 v[22:23], v[34:35], v[22:23]
	v_mov_b32_e32 v30, v40
	v_mov_b32_e32 v31, v28
	v_pk_add_f32 v[22:23], v[30:31], v[22:23]
	v_mov_b32_e32 v28, v41
	v_pk_add_f32 v[22:23], v[28:29], v[22:23]
	ds_bpermute_b32 v29, v199, v23
	ds_bpermute_b32 v28, v199, v22
	s_waitcnt lgkmcnt(0)
	v_pk_add_f32 v[22:23], v[22:23], v[28:29]
	ds_bpermute_b32 v29, v198, v23
	ds_bpermute_b32 v28, v198, v22
	s_waitcnt lgkmcnt(0)
	v_pk_add_f32 v[22:23], v[22:23], v[28:29]
	ds_bpermute_b32 v29, v197, v23
	ds_bpermute_b32 v28, v197, v22
	s_waitcnt lgkmcnt(0)
	v_pk_add_f32 v[22:23], v[22:23], v[28:29]
	ds_bpermute_b32 v29, v196, v23
	ds_bpermute_b32 v28, v196, v22
	s_waitcnt lgkmcnt(0)
	v_pk_add_f32 v[22:23], v[22:23], v[28:29]
	ds_bpermute_b32 v29, v195, v23
	ds_bpermute_b32 v28, v195, v22
	s_waitcnt lgkmcnt(0)
	v_pk_add_f32 v[22:23], v[22:23], v[28:29]
	s_nop 0
	v_pk_fma_f32 v[0:1], v[22:23], s[6:7], v[0:1] op_sel_hi:[1,0,0]
	v_lshl_add_u64 v[22:23], v[4:5], 0, v[128:129]
	v_mul_f32_e32 v8, 0x4b800000, v1
	v_cmp_gt_f32_e32 vcc, s82, v1
	s_nop 1
	v_cndmask_b32_e32 v1, v1, v8, vcc
	v_rsq_f32_e32 v1, v1
	s_nop 0
	v_mul_f32_e32 v4, 0x45800000, v1
	v_cndmask_b32_e32 v8, v1, v4, vcc
	v_pk_mul_f32 v[6:7], v[6:7], v[8:9] op_sel_hi:[1,0]
	v_pk_mul_f32 v[4:5], v[18:19], v[8:9] op_sel_hi:[1,0]
	s_waitcnt vmcnt(1)
	v_pk_mul_f32 v[6:7], v[10:11], v[6:7]
	v_pk_mul_f32 v[10:11], v[24:25], v[8:9] op_sel_hi:[1,0]
	s_waitcnt vmcnt(0)
	v_pk_mul_f32 v[4:5], v[14:15], v[4:5]
	v_pk_mul_f32 v[14:15], v[20:21], v[8:9] op_sel_hi:[1,0]
	v_pk_mul_f32 v[10:11], v[12:13], v[10:11]
	v_pk_mul_f32 v[14:15], v[16:17], v[14:15]
	v_cvt_pk_bf16_f32 v6, v6, v7
	v_cvt_pk_bf16_f32 v7, v10, v11
	v_add_co_u32_e32 v10, vcc, s44, v22
	v_cvt_pk_bf16_f32 v4, v4, v5
	v_cvt_pk_bf16_f32 v5, v14, v15
	v_addc_co_u32_e32 v11, vcc, 0, v23, vcc
	global_store_dwordx4 v[10:11], v[4:7], off offset:1536
	global_load_dwordx4 v[4:7], v9, s[0:1]
	s_nop 0
	global_load_dwordx4 v[8:11], v9, s[0:1] offset:16
	v_mul_f32_e32 v1, 0x4b800000, v0
	v_cmp_gt_f32_e32 vcc, s82, v0
	s_nop 1
	v_cndmask_b32_e32 v0, v0, v1, vcc
	v_rsq_f32_e32 v0, v0
	s_nop 0
	v_mul_f32_e32 v1, 0x45800000, v0
	v_cndmask_b32_e32 v0, v0, v1, vcc
	v_pk_mul_f32 v[12:13], v[26:27], v[0:1] op_sel_hi:[1,0]
	s_waitcnt vmcnt(1)
	v_pk_mul_f32 v[4:5], v[4:5], v[12:13]
	v_pk_mul_f32 v[12:13], v[38:39], v[0:1] op_sel_hi:[1,0]
	v_cvt_pk_bf16_f32 v4, v4, v5
	v_pk_mul_f32 v[6:7], v[6:7], v[12:13]
	s_nop 0
	v_cvt_pk_bf16_f32 v5, v6, v7
	v_pk_mul_f32 v[6:7], v[36:37], v[0:1] op_sel_hi:[1,0]
	v_pk_mul_f32 v[0:1], v[32:33], v[0:1] op_sel_hi:[1,0]
	s_waitcnt vmcnt(0)
	v_pk_mul_f32 v[6:7], v[8:9], v[6:7]
	v_pk_mul_f32 v[0:1], v[10:11], v[0:1]
	v_cvt_pk_bf16_f32 v6, v6, v7
	v_cvt_pk_bf16_f32 v7, v0, v1
	v_mad_i64_i32 v[0:1], s[0:1], v52, s56, v[2:3]
	v_lshl_add_u64 v[0:1], v[0:1], 0, v[128:129]
	v_add_co_u32_e32 v0, vcc, 0x1095000, v0
	s_nop 1
	v_addc_co_u32_e32 v1, vcc, 0, v1, vcc
	global_store_dwordx4 v[0:1], v[4:7], off offset:1536
	s_barrier
.LBB0_693:
	s_add_i32 s29, s29, s36
	s_waitcnt lgkmcnt(0)
	s_cmp_eq_u32 s9, 0x300
	s_cbranch_scc0 .Lrot_o_std
	s_cmpk_lg_i32 s36, 0x100
	s_cbranch_scc1 .Lrot_o_std
	s_cmp_lt_u32 s29, 0x300
	s_cbranch_scc1 .Lrot_o_nw
	s_sub_i32 s29, s29, 0x300
.Lrot_o_nw:
	s_and_b32 s0, s29, 0xff
	s_mul_i32 s1, s0, 171
	s_lshr_b32 s1, s1, 9
	s_mul_i32 s1, s1, 3
	s_sub_i32 s0, s0, s1
	s_lshr_b32 s1, s29, 8
	s_cmp_eq_u32 s0, s1
	s_cbranch_scc1 .Lcx_exit
	s_branch .LBB0_694
.Lrot_o_std:
	s_cmp_ge_i32 s29, s9
	s_cbranch_scc1 .Lcx_exit
